# phase 0: sc1 nt on all read-once loads (weights and x)
# baseline (speedup 1.0000x reference)
.LBB0_7:
	s_or_b64 exec, exec, s[0:1]
	v_readlane_b32 s0, v254, 2
	v_readlane_b32 s1, v254, 3
	s_cmpk_lg_i32 s1, 0xcfc7
	s_cbranch_scc1 .LBB0_19
	v_lshrrev_b32_e32 v1, 20, v0
	v_lshrrev_b32_e32 v0, 10, v0
	v_or_b32_e32 v0, v0, v1
	s_movk_i32 s0, 0x3ff
	v_and_or_b32 v0, v0, s0, v232
	v_cmp_eq_u32_e32 vcc, 0, v0
	s_barrier
	s_and_saveexec_b64 s[0:1], vcc
	s_cbranch_execz .LBB0_18
	buffer_wbl2 sc1
	s_waitcnt vmcnt(0)
	s_load_dwordx2 s[2:3], s[2:3], 0x58
	v_mov_b32_e32 v2, 0
	s_mov_b64 s[16:17], exec
	v_mbcnt_lo_u32_b32 v1, s16, 0
	v_mbcnt_hi_u32_b32 v1, s17, v1
	s_waitcnt lgkmcnt(0)
	global_load_dword v0, v2, s[2:3] offset:40 sc1 nt
	v_cmp_eq_u32_e32 vcc, 0, v1
	s_and_saveexec_b64 s[26:27], vcc
	s_cbranch_execz .LBB0_11
	s_bcnt1_i32_b64 s16, s[16:17]
	v_mov_b32_e32 v3, s16
	global_atomic_add v3, v2, v3, s[2:3] offset:32 sc0

.LBB0_21:
	v_lshl_add_u64 v[4:5], s[26:27], 2, v[24:25]
	global_load_dwordx4 v[0:3], v[4:5], off offset:16 sc1 nt
	s_nop 0
	global_load_dwordx4 v[4:7], v[4:5], off sc1 nt

.LBB0_36:
	s_cmpk_gt_u32 s27, 0xaff
	s_cselect_b64 s[16:17], -1, 0
	s_and_b64 s[92:93], s[16:17], exec
	s_cselect_b32 s27, 0x1600000, 0
	s_add_u32 s92, s22, s27
	s_addc_u32 s93, s23, 0
	s_lshl_b32 s73, s26, 6
	v_or_b32_e32 v2, s73, v30
	v_mov_b64_e32 v[0:1], s[92:93]
	s_movk_i32 s26, 0x5800
	v_mad_u64_u32 v[0:1], s[26:27], v2, s26, v[0:1]
	v_lshl_add_u64 v[0:1], s[6:7], 2, v[0:1]
	v_lshl_add_u64 v[0:1], v[0:1], 0, v[8:9]
	s_mov_b32 s6, 0xb000
	v_add_co_u32_e32 v2, vcc, s6, v0
	s_mov_b32 s6, 0x21000
	s_nop 0
	v_addc_co_u32_e32 v3, vcc, 0, v1, vcc
	v_add_co_u32_e32 v4, vcc, s43, v0
	s_and_b64 s[26:27], s[16:17], exec
	s_nop 0
	v_addc_co_u32_e32 v5, vcc, 0, v1, vcc
	v_add_co_u32_e32 v6, vcc, s6, v0
	s_mov_b32 s6, 0x37000
	s_nop 0
	v_addc_co_u32_e32 v7, vcc, 0, v1, vcc
	v_add_co_u32_e32 v48, vcc, s45, v0
	s_nop 1
	v_addc_co_u32_e32 v49, vcc, 0, v1, vcc
	v_add_co_u32_e32 v50, vcc, s6, v0
	s_mov_b32 s6, 0x42000
	s_nop 0
	v_addc_co_u32_e32 v51, vcc, 0, v1, vcc
	v_add_co_u32_e32 v52, vcc, s6, v0
	s_mov_b32 s6, 0x4d000
	s_nop 0
	v_addc_co_u32_e32 v53, vcc, 0, v1, vcc
	v_add_co_u32_e32 v54, vcc, s6, v0
	s_mov_b32 s6, 0x58000
	s_nop 0
	v_addc_co_u32_e32 v55, vcc, 0, v1, vcc
	global_load_dword v27, v[0:1], off sc1 nt
	global_load_dword v44, v[2:3], off sc1 nt
	global_load_dword v45, v[4:5], off sc1 nt
	global_load_dword v46, v[6:7], off sc1 nt
	global_load_dword v47, v[48:49], off sc1 nt
	s_nop 0
	global_load_dword v48, v[50:51], off sc1 nt
	global_load_dword v49, v[52:53], off sc1 nt
	s_nop 0
	global_load_dword v50, v[54:55], off sc1 nt
	v_add_co_u32_e32 v2, vcc, s6, v0
	s_mov_b32 s6, 0x63000
	s_nop 0
	v_addc_co_u32_e32 v3, vcc, 0, v1, vcc
	v_add_co_u32_e32 v4, vcc, s6, v0
	s_mov_b32 s6, 0x79000
	s_nop 0
	v_addc_co_u32_e32 v5, vcc, 0, v1, vcc
	v_add_co_u32_e32 v6, vcc, s47, v0
	s_nop 1
	v_addc_co_u32_e32 v7, vcc, 0, v1, vcc
	v_add_co_u32_e32 v54, vcc, s6, v0
	s_mov_b32 s6, 0x8f000
	s_nop 0
	v_addc_co_u32_e32 v55, vcc, 0, v1, vcc
	v_add_co_u32_e32 v56, vcc, s48, v0
	s_nop 1
	v_addc_co_u32_e32 v57, vcc, 0, v1, vcc
	v_add_co_u32_e32 v58, vcc, s6, v0
	s_mov_b32 s6, 0x9a000
	s_nop 0
	v_addc_co_u32_e32 v59, vcc, 0, v1, vcc
	v_add_co_u32_e32 v60, vcc, s6, v0
	s_mov_b32 s6, 0xa5000
	s_nop 0
	v_addc_co_u32_e32 v61, vcc, 0, v1, vcc
	v_add_co_u32_e32 v62, vcc, s6, v0
	s_mov_b32 s6, 0xb0000
	s_nop 0
	v_addc_co_u32_e32 v63, vcc, 0, v1, vcc
	global_load_dword v51, v[2:3], off sc1 nt
	global_load_dword v52, v[4:5], off sc1 nt
	global_load_dword v53, v[6:7], off sc1 nt
	s_nop 0
	global_load_dword v54, v[54:55], off sc1 nt
	s_nop 0
	global_load_dword v55, v[56:57], off sc1 nt
	s_nop 0
	global_load_dword v56, v[58:59], off sc1 nt
	global_load_dword v57, v[60:61], off sc1 nt
	s_nop 0
	global_load_dword v58, v[62:63], off sc1 nt
	v_add_co_u32_e32 v2, vcc, s6, v0
	s_cselect_b32 s6, 0x1000, 0
	s_nop 0
	v_addc_co_u32_e32 v3, vcc, 0, v1, vcc
	v_add_co_u32_e32 v4, vcc, s49, v0
	s_add_u32 s26, s20, s6
	s_nop 0
	v_addc_co_u32_e32 v5, vcc, 0, v1, vcc
	v_add_co_u32_e32 v6, vcc, s50, v0
	s_addc_u32 s27, s21, 0
	s_nop 0
	v_addc_co_u32_e32 v7, vcc, 0, v1, vcc
	v_add_co_u32_e32 v62, vcc, s51, v0
	s_cmp_eq_u64 s[26:27], 0
	s_nop 0
	v_addc_co_u32_e32 v63, vcc, 0, v1, vcc
	v_add_co_u32_e32 v64, vcc, s52, v0
	s_mov_b32 s6, s73
	s_nop 0
	v_addc_co_u32_e32 v65, vcc, 0, v1, vcc
	v_add_co_u32_e32 v66, vcc, s53, v0
	s_nop 1
	v_addc_co_u32_e32 v67, vcc, 0, v1, vcc
	v_add_co_u32_e32 v68, vcc, s54, v0
	s_nop 1
	v_addc_co_u32_e32 v69, vcc, 0, v1, vcc
	v_add_co_u32_e32 v70, vcc, s55, v0
	s_nop 1
	v_addc_co_u32_e32 v71, vcc, 0, v1, vcc
	global_load_dword v59, v[2:3], off sc1 nt
	global_load_dword v60, v[4:5], off sc1 nt
	global_load_dword v61, v[6:7], off sc1 nt
	s_nop 0
	global_load_dword v62, v[62:63], off sc1 nt
	s_nop 0
	global_load_dword v63, v[64:65], off sc1 nt
	s_nop 0
	global_load_dword v64, v[66:67], off sc1 nt
	global_load_dword v65, v[68:69], off sc1 nt
	s_nop 0
	global_load_dword v66, v[70:71], off sc1 nt
	v_add_co_u32_e32 v2, vcc, s56, v0
	s_nop 1
	v_addc_co_u32_e32 v3, vcc, 0, v1, vcc
	v_add_co_u32_e32 v4, vcc, s57, v0
	s_nop 1
	v_addc_co_u32_e32 v5, vcc, 0, v1, vcc
	v_add_co_u32_e32 v6, vcc, s58, v0
	s_nop 1
	v_addc_co_u32_e32 v7, vcc, 0, v1, vcc
	v_add_co_u32_e32 v70, vcc, s59, v0
	s_nop 1
	v_addc_co_u32_e32 v71, vcc, 0, v1, vcc
	v_add_co_u32_e32 v72, vcc, s60, v0
	s_nop 1
	v_addc_co_u32_e32 v73, vcc, 0, v1, vcc
	v_add_co_u32_e32 v74, vcc, 0x13f000, v0
	s_nop 1
	v_addc_co_u32_e32 v75, vcc, 0, v1, vcc
	v_add_co_u32_e32 v76, vcc, 0x14a000, v0
	s_nop 1
	v_addc_co_u32_e32 v77, vcc, 0, v1, vcc
	v_add_co_u32_e32 v0, vcc, 0x155000, v0
	s_nop 1
	v_addc_co_u32_e32 v1, vcc, 0, v1, vcc
	global_load_dword v67, v[2:3], off sc1 nt
	global_load_dword v68, v[4:5], off sc1 nt
	global_load_dword v69, v[6:7], off sc1 nt
	s_nop 0
	global_load_dword v70, v[70:71], off sc1 nt
	s_nop 0
	global_load_dword v71, v[72:73], off sc1 nt
	s_nop 0
	global_load_dword v72, v[74:75], off sc1 nt
	global_load_dword v73, v[76:77], off sc1 nt
	s_nop 0
	global_load_dword v74, v[0:1], off sc1 nt
	s_cbranch_scc1 .LBB0_38
	s_lshl_b64 s[92:93], s[6:7], 2
	s_add_u32 s26, s26, s92
	s_addc_u32 s27, s27, s93
	v_lshlrev_b32_e32 v4, 2, v10
	global_load_dwordx4 v[0:3], v4, s[26:27] offset:16 sc1 nt
	s_nop 0
	global_load_dwordx4 v[4:7], v4, s[26:27] sc1 nt
	s_branch .LBB0_39

.LBB0_44:
	s_andn2_b64 vcc, exec, s[16:17]
	s_cbranch_vccnz .LBB0_49
	s_and_b32 s17, s40, 0x3fc0
	s_addk_i32 s17, 0xd000
	s_and_b32 s16, s38, 0x3e0
	v_or_b32_e32 v2, s17, v30
	v_mov_b64_e32 v[0:1], s[14:15]
	v_mad_u64_u32 v[0:1], s[26:27], v2, s61, v[0:1]
	s_lshl_b32 s6, s16, 2
	v_lshl_add_u64 v[0:1], v[0:1], 0, s[6:7]
	v_lshl_add_u64 v[0:1], v[0:1], 0, v[8:9]
	v_add_co_u32_e32 v2, vcc, 0x2000, v0
	s_mov_b32 s6, s17
	s_nop 0
	v_addc_co_u32_e32 v3, vcc, 0, v1, vcc
	v_add_co_u32_e32 v4, vcc, 0x8000, v0
	s_nop 1
	v_addc_co_u32_e32 v5, vcc, 0, v1, vcc
	v_add_co_u32_e32 v6, vcc, 0xe000, v0
	s_nop 1
	v_addc_co_u32_e32 v7, vcc, 0, v1, vcc
	v_add_co_u32_e32 v46, vcc, 0x14000, v0
	s_nop 1
	v_addc_co_u32_e32 v47, vcc, 0, v1, vcc
	v_add_co_u32_e32 v48, vcc, 0x1a000, v0
	s_nop 1
	v_addc_co_u32_e32 v49, vcc, 0, v1, vcc
	v_add_co_u32_e32 v50, vcc, 0x20000, v0
	s_nop 1
	v_addc_co_u32_e32 v51, vcc, 0, v1, vcc
	v_add_co_u32_e32 v52, vcc, 0x26000, v0
	s_nop 1
	v_addc_co_u32_e32 v53, vcc, 0, v1, vcc
	v_add_co_u32_e32 v54, vcc, 0x2c000, v0
	s_nop 1
	v_addc_co_u32_e32 v55, vcc, 0, v1, vcc
	global_load_dword v27, v[2:3], off sc1 nt
	global_load_dword v44, v[4:5], off offset:128 sc1 nt
	global_load_dword v45, v[6:7], off offset:256 sc1 nt
	s_nop 0
	global_load_dword v46, v[46:47], off offset:384 sc1 nt
	s_nop 0
	global_load_dword v47, v[48:49], off offset:512 sc1 nt
	s_nop 0
	global_load_dword v48, v[50:51], off offset:640 sc1 nt
	global_load_dword v49, v[52:53], off offset:768 sc1 nt
	s_nop 0
	global_load_dword v50, v[54:55], off offset:896 sc1 nt
	v_add_co_u32_e32 v2, vcc, 0x32000, v0
	s_nop 1
	v_addc_co_u32_e32 v3, vcc, 0, v1, vcc
	v_add_co_u32_e32 v4, vcc, 0x38000, v0
	s_nop 1
	v_addc_co_u32_e32 v5, vcc, 0, v1, vcc
	v_add_co_u32_e32 v6, vcc, 0x3e000, v0
	s_nop 1
	v_addc_co_u32_e32 v7, vcc, 0, v1, vcc
	v_add_co_u32_e32 v54, vcc, 0x44000, v0
	s_nop 1
	v_addc_co_u32_e32 v55, vcc, 0, v1, vcc
	v_add_co_u32_e32 v56, vcc, 0x4a000, v0
	s_nop 1
	v_addc_co_u32_e32 v57, vcc, 0, v1, vcc
	v_add_co_u32_e32 v58, vcc, 0x50000, v0
	s_nop 1
	v_addc_co_u32_e32 v59, vcc, 0, v1, vcc
	v_add_co_u32_e32 v60, vcc, 0x56000, v0
	s_nop 1
	v_addc_co_u32_e32 v61, vcc, 0, v1, vcc
	v_add_co_u32_e32 v62, vcc, 0x5c000, v0
	s_nop 1
	v_addc_co_u32_e32 v63, vcc, 0, v1, vcc
	global_load_dword v51, v[2:3], off offset:1024 sc1 nt
	global_load_dword v52, v[4:5], off offset:1152 sc1 nt
	global_load_dword v53, v[6:7], off offset:1280 sc1 nt
	s_nop 0
	global_load_dword v54, v[54:55], off offset:1408 sc1 nt
	s_nop 0
	global_load_dword v55, v[56:57], off offset:1536 sc1 nt
	s_nop 0
	global_load_dword v56, v[58:59], off offset:1664 sc1 nt
	global_load_dword v57, v[60:61], off offset:1792 sc1 nt
	s_nop 0
	global_load_dword v58, v[62:63], off offset:1920 sc1 nt
	v_add_co_u32_e32 v2, vcc, 0x62000, v0
	s_nop 1
	v_addc_co_u32_e32 v3, vcc, 0, v1, vcc
	v_add_co_u32_e32 v4, vcc, 0x68000, v0
	s_nop 1
	v_addc_co_u32_e32 v5, vcc, 0, v1, vcc
	v_add_co_u32_e32 v6, vcc, s47, v0
	s_nop 1
	v_addc_co_u32_e32 v7, vcc, 0, v1, vcc
	v_add_co_u32_e32 v62, vcc, 0x74000, v0
	s_nop 1
	v_addc_co_u32_e32 v63, vcc, 0, v1, vcc
	v_add_co_u32_e32 v64, vcc, 0x7a000, v0
	s_nop 1
	v_addc_co_u32_e32 v65, vcc, 0, v1, vcc
	v_add_co_u32_e32 v66, vcc, 0x80000, v0
	s_nop 1
	v_addc_co_u32_e32 v67, vcc, 0, v1, vcc
	v_add_co_u32_e32 v68, vcc, 0x86000, v0
	s_nop 1
	v_addc_co_u32_e32 v69, vcc, 0, v1, vcc
	v_add_co_u32_e32 v70, vcc, 0x8c000, v0
	s_nop 1
	v_addc_co_u32_e32 v71, vcc, 0, v1, vcc
	global_load_dword v59, v[2:3], off offset:2048 sc1 nt
	global_load_dword v60, v[4:5], off offset:2176 sc1 nt
	global_load_dword v61, v[6:7], off offset:2304 sc1 nt
	s_nop 0
	global_load_dword v62, v[62:63], off offset:2432 sc1 nt
	s_nop 0
	global_load_dword v63, v[64:65], off offset:2560 sc1 nt
	s_nop 0
	global_load_dword v64, v[66:67], off offset:2688 sc1 nt
	global_load_dword v65, v[68:69], off offset:2816 sc1 nt
	s_nop 0
	global_load_dword v66, v[70:71], off offset:2944 sc1 nt
	v_add_co_u32_e32 v2, vcc, 0x92000, v0
	s_nop 1
	v_addc_co_u32_e32 v3, vcc, 0, v1, vcc
	v_add_co_u32_e32 v4, vcc, 0x98000, v0
	s_nop 1
	v_addc_co_u32_e32 v5, vcc, 0, v1, vcc
	v_add_co_u32_e32 v6, vcc, 0x9e000, v0
	s_nop 1
	v_addc_co_u32_e32 v7, vcc, 0, v1, vcc
	v_add_co_u32_e32 v70, vcc, 0xa4000, v0
	s_nop 1
	v_addc_co_u32_e32 v71, vcc, 0, v1, vcc
	v_add_co_u32_e32 v72, vcc, 0xaa000, v0
	s_nop 1
	v_addc_co_u32_e32 v73, vcc, 0, v1, vcc
	v_add_co_u32_e32 v74, vcc, 0xb0000, v0
	s_nop 1
	v_addc_co_u32_e32 v75, vcc, 0, v1, vcc
	v_add_co_u32_e32 v76, vcc, 0xb6000, v0
	s_nop 1
	v_addc_co_u32_e32 v77, vcc, 0, v1, vcc
	v_add_co_u32_e32 v0, vcc, 0xbc000, v0
	s_nop 1
	v_addc_co_u32_e32 v1, vcc, 0, v1, vcc
	global_load_dword v67, v[2:3], off offset:3072 sc1 nt
	global_load_dword v68, v[4:5], off offset:3200 sc1 nt
	global_load_dword v69, v[6:7], off offset:3328 sc1 nt
	s_nop 0
	global_load_dword v70, v[70:71], off offset:3456 sc1 nt
	s_nop 0
	global_load_dword v71, v[72:73], off offset:3584 sc1 nt
	s_nop 0
	global_load_dword v72, v[74:75], off offset:3712 sc1 nt
	global_load_dword v73, v[76:77], off offset:3840 sc1 nt
	s_nop 0
	global_load_dword v74, v[0:1], off offset:3968 sc1 nt
	s_andn2_b64 vcc, exec, s[0:1]
	s_cbranch_vccnz .LBB0_47
	v_lshl_add_u64 v[4:5], s[6:7], 2, v[22:23]
	global_load_dwordx4 v[0:3], v[4:5], off offset:16 sc1 nt
	s_nop 0
	global_load_dwordx4 v[4:7], v[4:5], off sc1 nt
	s_branch .LBB0_48

.LBB0_50:
	s_andn2_b64 vcc, exec, s[16:17]
	s_cbranch_vccnz .LBB0_55
	s_and_b32 s17, s90, 0x1fc0
	s_addk_i32 s17, 0xec00
	s_and_b32 s16, s38, 0x7e0
	v_or_b32_e32 v2, s17, v30
	v_mov_b64_e32 v[0:1], s[14:15]
	v_mad_u64_u32 v[0:1], s[26:27], v2, s61, v[0:1]
	s_lshl_b32 s6, s16, 2
	v_lshl_add_u64 v[0:1], v[0:1], 0, s[6:7]
	v_lshl_add_u64 v[0:1], v[0:1], 0, v[8:9]
	v_add_co_u32_e32 v2, vcc, 0x6000, v0
	s_mov_b32 s6, s17
	s_nop 0
	v_addc_co_u32_e32 v3, vcc, 0, v1, vcc
	v_add_co_u32_e32 v4, vcc, 0xc000, v0
	s_nop 1
	v_addc_co_u32_e32 v5, vcc, 0, v1, vcc
	v_add_co_u32_e32 v6, vcc, 0x12000, v0
	s_nop 1
	v_addc_co_u32_e32 v7, vcc, 0, v1, vcc
	v_add_co_u32_e32 v48, vcc, 0x18000, v0
	s_nop 1
	v_addc_co_u32_e32 v49, vcc, 0, v1, vcc
	v_add_co_u32_e32 v50, vcc, 0x1e000, v0
	s_nop 1
	v_addc_co_u32_e32 v51, vcc, 0, v1, vcc
	v_add_co_u32_e32 v52, vcc, 0x24000, v0
	s_nop 1
	v_addc_co_u32_e32 v53, vcc, 0, v1, vcc
	v_add_co_u32_e32 v54, vcc, 0x2a000, v0
	s_nop 1
	v_addc_co_u32_e32 v55, vcc, 0, v1, vcc
	global_load_dword v27, v[0:1], off sc1 nt
	global_load_dword v44, v[2:3], off offset:128 sc1 nt
	global_load_dword v45, v[4:5], off offset:256 sc1 nt
	global_load_dword v46, v[6:7], off offset:384 sc1 nt
	global_load_dword v47, v[48:49], off offset:512 sc1 nt
	s_nop 0
	global_load_dword v48, v[50:51], off offset:640 sc1 nt
	global_load_dword v49, v[52:53], off offset:768 sc1 nt
	s_nop 0
	global_load_dword v50, v[54:55], off offset:896 sc1 nt
	v_add_co_u32_e32 v2, vcc, 0x30000, v0
	s_nop 1
	v_addc_co_u32_e32 v3, vcc, 0, v1, vcc
	v_add_co_u32_e32 v4, vcc, 0x36000, v0
	s_nop 1
	v_addc_co_u32_e32 v5, vcc, 0, v1, vcc
	v_add_co_u32_e32 v6, vcc, 0x3c000, v0
	s_nop 1
	v_addc_co_u32_e32 v7, vcc, 0, v1, vcc
	v_add_co_u32_e32 v54, vcc, 0x42000, v0
	s_nop 1
	v_addc_co_u32_e32 v55, vcc, 0, v1, vcc
	v_add_co_u32_e32 v56, vcc, 0x48000, v0
	s_nop 1
	v_addc_co_u32_e32 v57, vcc, 0, v1, vcc
	v_add_co_u32_e32 v58, vcc, 0x4e000, v0
	s_nop 1
	v_addc_co_u32_e32 v59, vcc, 0, v1, vcc
	v_add_co_u32_e32 v60, vcc, 0x54000, v0
	s_nop 1
	v_addc_co_u32_e32 v61, vcc, 0, v1, vcc
	v_add_co_u32_e32 v62, vcc, 0x5a000, v0
	s_nop 1
	v_addc_co_u32_e32 v63, vcc, 0, v1, vcc
	global_load_dword v51, v[2:3], off offset:1024 sc1 nt
	global_load_dword v52, v[4:5], off offset:1152 sc1 nt
	global_load_dword v53, v[6:7], off offset:1280 sc1 nt
	s_nop 0
	global_load_dword v54, v[54:55], off offset:1408 sc1 nt
	s_nop 0
	global_load_dword v55, v[56:57], off offset:1536 sc1 nt
	s_nop 0
	global_load_dword v56, v[58:59], off offset:1664 sc1 nt
	global_load_dword v57, v[60:61], off offset:1792 sc1 nt
	s_nop 0
	global_load_dword v58, v[62:63], off offset:1920 sc1 nt
	v_add_co_u32_e32 v2, vcc, 0x60000, v0
	s_nop 1
	v_addc_co_u32_e32 v3, vcc, 0, v1, vcc
	v_add_co_u32_e32 v4, vcc, 0x66000, v0
	s_nop 1
	v_addc_co_u32_e32 v5, vcc, 0, v1, vcc
	v_add_co_u32_e32 v6, vcc, 0x6c000, v0
	s_nop 1
	v_addc_co_u32_e32 v7, vcc, 0, v1, vcc
	v_add_co_u32_e32 v62, vcc, 0x72000, v0
	s_nop 1
	v_addc_co_u32_e32 v63, vcc, 0, v1, vcc
	v_add_co_u32_e32 v64, vcc, 0x78000, v0
	s_nop 1
	v_addc_co_u32_e32 v65, vcc, 0, v1, vcc
	v_add_co_u32_e32 v66, vcc, 0x7e000, v0
	s_nop 1
	v_addc_co_u32_e32 v67, vcc, 0, v1, vcc
	v_add_co_u32_e32 v68, vcc, s48, v0
	s_nop 1
	v_addc_co_u32_e32 v69, vcc, 0, v1, vcc
	v_add_co_u32_e32 v70, vcc, 0x8a000, v0
	s_nop 1
	v_addc_co_u32_e32 v71, vcc, 0, v1, vcc
	global_load_dword v59, v[2:3], off offset:2048 sc1 nt
	global_load_dword v60, v[4:5], off offset:2176 sc1 nt
	global_load_dword v61, v[6:7], off offset:2304 sc1 nt
	s_nop 0
	global_load_dword v62, v[62:63], off offset:2432 sc1 nt
	s_nop 0
	global_load_dword v63, v[64:65], off offset:2560 sc1 nt
	s_nop 0
	global_load_dword v64, v[66:67], off offset:2688 sc1 nt
	global_load_dword v65, v[68:69], off offset:2816 sc1 nt
	s_nop 0
	global_load_dword v66, v[70:71], off offset:2944 sc1 nt
	v_add_co_u32_e32 v2, vcc, 0x90000, v0
	s_nop 1
	v_addc_co_u32_e32 v3, vcc, 0, v1, vcc
	v_add_co_u32_e32 v4, vcc, 0x96000, v0
	s_nop 1
	v_addc_co_u32_e32 v5, vcc, 0, v1, vcc
	v_add_co_u32_e32 v6, vcc, 0x9c000, v0
	s_nop 1
	v_addc_co_u32_e32 v7, vcc, 0, v1, vcc
	v_add_co_u32_e32 v70, vcc, 0xa2000, v0
	s_nop 1
	v_addc_co_u32_e32 v71, vcc, 0, v1, vcc
	v_add_co_u32_e32 v72, vcc, 0xa8000, v0
	s_nop 1
	v_addc_co_u32_e32 v73, vcc, 0, v1, vcc
	v_add_co_u32_e32 v74, vcc, 0xae000, v0
	s_nop 1
	v_addc_co_u32_e32 v75, vcc, 0, v1, vcc
	v_add_co_u32_e32 v76, vcc, 0xb4000, v0
	s_nop 1
	v_addc_co_u32_e32 v77, vcc, 0, v1, vcc
	v_add_co_u32_e32 v0, vcc, 0xba000, v0
	s_nop 1
	v_addc_co_u32_e32 v1, vcc, 0, v1, vcc
	global_load_dword v67, v[2:3], off offset:3072 sc1 nt
	global_load_dword v68, v[4:5], off offset:3200 sc1 nt
	global_load_dword v69, v[6:7], off offset:3328 sc1 nt
	s_nop 0
	global_load_dword v70, v[70:71], off offset:3456 sc1 nt
	s_nop 0
	global_load_dword v71, v[72:73], off offset:3584 sc1 nt
	s_nop 0
	global_load_dword v72, v[74:75], off offset:3712 sc1 nt
	global_load_dword v73, v[76:77], off offset:3840 sc1 nt
	s_nop 0
	global_load_dword v74, v[0:1], off offset:3968 sc1 nt
	s_andn2_b64 vcc, exec, s[0:1]
	s_cbranch_vccnz .LBB0_53
	v_lshl_add_u64 v[4:5], s[6:7], 2, v[22:23]
	global_load_dwordx4 v[0:3], v[4:5], off offset:16 sc1 nt
	s_nop 0
	global_load_dwordx4 v[4:7], v[4:5], off sc1 nt
	s_branch .LBB0_54

.LBB0_66:
	v_ashrrev_i32_e32 v14, 10, v6
	v_and_b32_e32 v2, 0x3ff, v6
	v_ashrrev_i32_e32 v15, 31, v14
	v_mad_u64_u32 v[18:19], s[26:27], v2, s21, v[0:1]
	v_ashrrev_i32_e32 v16, 10, v7
	v_and_b32_e32 v5, 0x3ff, v7
	v_lshl_add_u64 v[18:19], v[14:15], 2, v[18:19]
	v_ashrrev_i32_e32 v17, 31, v16
	v_mad_u64_u32 v[20:21], s[26:27], v5, s21, v[0:1]
	v_add_co_u32_e32 v18, vcc, s22, v18
	v_lshl_add_u64 v[20:21], v[16:17], 2, v[20:21]
	s_nop 0
	v_addc_co_u32_e32 v19, vcc, 0, v19, vcc
	v_lshlrev_b32_e32 v13, 2, v2
	v_lshlrev_b32_e32 v24, 2, v5
	v_add_co_u32_e32 v20, vcc, s22, v20
	global_load_dword v22, v13, s[12:13] sc1 nt
	global_load_dword v23, v24, s[12:13] sc1 nt
	v_addc_co_u32_e32 v21, vcc, 0, v21, vcc
	global_load_dword v24, v[18:19], off sc1 nt
	global_load_dword v25, v[20:21], off sc1 nt
	v_lshlrev_b64 v[14:15], 11, v[14:15]
	v_add_u32_e32 v12, -2, v12
	v_lshlrev_b32_e32 v2, 1, v2
	v_lshl_add_u64 v[14:15], s[8:9], 0, v[14:15]
	v_cmp_eq_u32_e32 vcc, 0, v12
	v_lshlrev_b64 v[16:17], 11, v[16:17]
	v_lshl_add_u64 v[14:15], v[14:15], 0, v[2:3]
	s_or_b64 s[18:19], vcc, s[18:19]
	v_lshl_add_u64 v[16:17], s[8:9], 0, v[16:17]
	v_lshlrev_b32_e32 v2, 1, v5
	v_add_co_u32_e32 v14, vcc, s24, v14
	v_lshl_add_u64 v[16:17], v[16:17], 0, v[2:3]
	s_nop 0
	v_addc_co_u32_e32 v15, vcc, 0, v15, vcc
	v_add_u32_e32 v7, s20, v7
	v_add_u32_e32 v6, s1, v6
	v_add_co_u32_e32 v16, vcc, 0x400000, v16
	s_waitcnt vmcnt(0)
	v_pk_mul_f32 v[18:19], v[24:25], v[22:23]
	s_nop 0
	v_and_b32_sdwa v5, v18, v10 dst_sel:DWORD dst_unused:UNUSED_PAD src0_sel:WORD_1 src1_sel:DWORD
	v_and_b32_sdwa v2, v19, v10 dst_sel:DWORD dst_unused:UNUSED_PAD src0_sel:WORD_1 src1_sel:DWORD
	v_add3_u32 v5, v18, v5, s23
	v_addc_co_u32_e32 v17, vcc, 0, v17, vcc
	v_add3_u32 v2, v19, v2, s23
	global_store_short_d16_hi v[14:15], v5, off
	global_store_short_d16_hi v[16:17], v2, off
	s_andn2_b64 exec, exec, s[18:19]
	s_cbranch_execnz .LBB0_66
	s_or_b64 exec, exec, s[18:19]
	v_mad_u64_u32 v[0:1], s[18:19], v9, s0, v[4:5]
	v_cmp_ne_u32_e32 vcc, v8, v9
	s_orn2_b64 s[18:19], vcc, exec

.LBB0_71:
	v_ashrrev_i32_e32 v8, 10, v0
	v_and_b32_e32 v1, 0x3ff, v0
	v_ashrrev_i32_e32 v9, 31, v8
	v_mad_u64_u32 v[12:13], s[14:15], v1, s1, v[2:3]
	v_lshl_add_u64 v[12:13], v[8:9], 2, v[12:13]
	v_add_co_u32_e32 v12, vcc, 0x3000, v12
	v_lshlrev_b32_e32 v5, 2, v1
	s_nop 0
	v_addc_co_u32_e32 v13, vcc, 0, v13, vcc
	global_load_dword v5, v5, s[12:13] sc1 nt
	v_lshlrev_b64 v[8:9], 11, v[8:9]
	global_load_dword v10, v[12:13], off sc1 nt
	v_add_u32_e32 v0, s0, v0
	v_lshlrev_b32_e32 v6, 1, v1
	v_lshl_add_u64 v[8:9], s[8:9], 0, v[8:9]
	v_cmp_lt_i32_e32 vcc, s11, v0
	v_lshl_add_u64 v[8:9], v[8:9], 0, v[6:7]
	s_or_b64 s[2:3], vcc, s[2:3]
	v_add_co_u32_e32 v8, vcc, 0x400000, v8
	s_waitcnt vmcnt(0)
	v_mul_f32_e32 v1, v10, v5
	v_bfe_u32 v5, v1, 16, 1
	v_addc_co_u32_e32 v9, vcc, 0, v9, vcc
	v_add3_u32 v1, v1, v5, s10
	global_store_short_d16_hi v[8:9], v1, off
	s_andn2_b64 exec, exec, s[2:3]
	s_cbranch_execnz .LBB0_71

.LBB0_81:
	v_add_co_u32_e32 v0, vcc, 0xffffd000, v70
	s_and_b32 s4, s0, 0xfffff000
	s_nop 0
	v_addc_co_u32_e32 v1, vcc, -1, v71, vcc
	global_load_dwordx4 v[60:63], v[0:1], off offset:-3072 sc1 nt
	s_waitcnt lgkmcnt(3)
	global_load_dwordx4 v[56:59], v[0:1], off offset:-2048 sc1 nt
	s_waitcnt lgkmcnt(2)
	global_load_dwordx4 v[48:51], v[0:1], off offset:-1024 sc1 nt
	s_waitcnt lgkmcnt(0)
	global_load_dwordx4 v[44:47], v[0:1], off sc1 nt
	v_add_co_u32_e32 v0, vcc, 0xffffe000, v70
	s_ashr_i32 s5, s4, 31
	s_nop 0
	v_addc_co_u32_e32 v1, vcc, -1, v71, vcc
	global_load_dwordx4 v[40:43], v[0:1], off offset:-3072 sc1 nt
	global_load_dwordx4 v[36:39], v[0:1], off offset:-2048 sc1 nt
	global_load_dwordx4 v[32:35], v[0:1], off offset:-1024 sc1 nt
	global_load_dwordx4 v[28:31], v[0:1], off sc1 nt
	v_add_co_u32_e32 v72, vcc, 0xfffff000, v70
	s_waitcnt vmcnt(7)
	v_mul_f32_e32 v64, v61, v61
	v_addc_co_u32_e32 v73, vcc, -1, v71, vcc
	global_load_dwordx4 v[20:23], v[72:73], off offset:-3072 sc1 nt
	global_load_dwordx4 v[24:27], v[72:73], off offset:-2048 sc1 nt
	global_load_dwordx4 v[16:19], v[72:73], off offset:-1024 sc1 nt
	global_load_dwordx4 v[12:15], v[70:71], off offset:-4096 sc1 nt
	global_load_dwordx4 v[8:11], v[70:71], off offset:-3072 sc1 nt
	global_load_dwordx4 v[4:7], v[70:71], off offset:-2048 sc1 nt
	global_load_dwordx4 v[0:3], v[70:71], off offset:-1024 sc1 nt
	global_load_dwordx4 v[52:55], v[70:71], off sc1 nt
	v_mul_f32_e32 v73, v63, v63
	v_cvt_pk_bf16_f32 v72, v60, v61
	s_waitcnt vmcnt(14)
	v_mul_f32_e32 v61, v57, v57
	v_mul_f32_e32 v84, v59, v59
	s_waitcnt vmcnt(13)
	v_mul_f32_e32 v85, v49, v49
	v_mul_f32_e32 v86, v51, v51
	s_waitcnt vmcnt(12)
	v_mul_f32_e32 v87, v45, v45
	v_mul_f32_e32 v88, v47, v47
	v_fmac_f32_e32 v64, v60, v60
	v_fmac_f32_e32 v73, v62, v62
	v_fmac_f32_e32 v61, v56, v56
	v_fmac_f32_e32 v84, v58, v58
	v_fmac_f32_e32 v85, v48, v48
	v_fmac_f32_e32 v86, v50, v50
	v_fmac_f32_e32 v87, v44, v44
	v_fmac_f32_e32 v88, v46, v46
	s_waitcnt vmcnt(11)
	v_mul_f32_e32 v60, v41, v41
	v_mul_f32_e32 v89, v43, v43
	s_waitcnt vmcnt(10)
	v_mul_f32_e32 v90, v37, v37
	v_mul_f32_e32 v91, v39, v39
	v_add_f32_e32 v64, v64, v73
	v_add_f32_e32 v61, v61, v84
	v_add_f32_e32 v73, v85, v86
	v_add_f32_e32 v84, v87, v88
	v_fmac_f32_e32 v60, v40, v40
	v_fmac_f32_e32 v89, v42, v42
	v_fmac_f32_e32 v90, v36, v36
	v_fmac_f32_e32 v91, v38, v38
	v_add_f32_e32 v61, v64, v61
	v_add_f32_e32 v60, v60, v89
	v_add_f32_e32 v64, v90, v91
	v_add_f32_e32 v61, v61, v73
	v_add_f32_e32 v60, v60, v64
	v_add_f32_e32 v61, v61, v84
	s_waitcnt vmcnt(9)
	v_mul_f32_e32 v92, v33, v33
	v_mul_f32_e32 v93, v35, v35
	s_waitcnt vmcnt(8)
	v_mul_f32_e32 v94, v29, v29
	v_mul_f32_e32 v95, v31, v31
	v_fmac_f32_e32 v92, v32, v32
	v_fmac_f32_e32 v93, v34, v34
	v_fmac_f32_e32 v94, v28, v28
	v_fmac_f32_e32 v95, v30, v30
	v_add_f32_e32 v89, v92, v93
	v_add_f32_e32 v90, v94, v95
	v_add_f32_e32 v60, v60, v89
	v_add_f32_e32 v60, v60, v90
	s_waitcnt vmcnt(7)
	v_mul_f32_e32 v85, v21, v21
	v_mul_f32_e32 v86, v23, v23
	s_waitcnt vmcnt(6)
	v_mul_f32_e32 v87, v25, v25
	v_mul_f32_e32 v88, v27, v27
	v_fmac_f32_e32 v85, v20, v20
	v_fmac_f32_e32 v86, v22, v22
	v_fmac_f32_e32 v87, v24, v24
	v_fmac_f32_e32 v88, v26, v26
	v_add_f32_e32 v64, v85, v86
	v_add_f32_e32 v73, v87, v88
	v_add_f32_e32 v64, v64, v73
	s_waitcnt vmcnt(5)
	v_mul_f32_e32 v73, v17, v17
	v_mul_f32_e32 v84, v19, v19
	v_fmac_f32_e32 v73, v16, v16
	v_fmac_f32_e32 v84, v18, v18
	v_add_f32_e32 v73, v73, v84
	v_add_f32_e32 v64, v64, v73
	s_waitcnt vmcnt(4)
	v_mul_f32_e32 v73, v13, v13
	v_mul_f32_e32 v84, v15, v15
	v_fmac_f32_e32 v73, v12, v12
	v_fmac_f32_e32 v84, v14, v14
	v_add_f32_e32 v73, v73, v84
	v_add_f32_e32 v64, v64, v73
	s_waitcnt vmcnt(3)
	v_mul_f32_e32 v73, v9, v9
	v_mul_f32_e32 v84, v11, v11
	v_fmac_f32_e32 v73, v8, v8
	v_fmac_f32_e32 v84, v10, v10
	v_add_f32_e32 v73, v73, v84
	s_waitcnt vmcnt(2)
	v_mul_f32_e32 v84, v5, v5
	v_mul_f32_e32 v85, v7, v7
	v_fmac_f32_e32 v84, v4, v4
	v_fmac_f32_e32 v85, v6, v6
	v_add_f32_e32 v84, v84, v85
	v_add_f32_e32 v73, v73, v84
	s_waitcnt vmcnt(1)
	v_mul_f32_e32 v84, v1, v1
	v_mul_f32_e32 v85, v3, v3
	v_fmac_f32_e32 v84, v0, v0
	v_fmac_f32_e32 v85, v2, v2
	v_add_f32_e32 v84, v84, v85
	v_add_f32_e32 v73, v73, v84
	s_waitcnt vmcnt(0)
	v_mul_f32_e32 v84, v53, v53
	v_mul_f32_e32 v85, v55, v55
	v_fmac_f32_e32 v84, v52, v52
	v_fmac_f32_e32 v85, v54, v54
	v_add_f32_e32 v84, v84, v85
	v_add_f32_e32 v84, v73, v84
	v_cvt_pk_bf16_f32 v73, v62, v63
	v_add_f32_dpp v61, v61, v61 quad_perm:[1,0,3,2] row_mask:0xf bank_mask:0xf
	v_add_f32_dpp v62, v60, v60 quad_perm:[1,0,3,2] row_mask:0xf bank_mask:0xf
	v_add_f32_dpp v63, v64, v64 quad_perm:[1,0,3,2] row_mask:0xf bank_mask:0xf
	v_add_f32_dpp v64, v84, v84 quad_perm:[1,0,3,2] row_mask:0xf bank_mask:0xf
	v_cvt_pk_bf16_f32 v60, v56, v57
	v_add_f32_dpp v56, v61, v61 quad_perm:[2,3,0,1] row_mask:0xf bank_mask:0xf
	v_add_f32_dpp v57, v62, v62 quad_perm:[2,3,0,1] row_mask:0xf bank_mask:0xf
	v_add_f32_dpp v62, v63, v63 quad_perm:[2,3,0,1] row_mask:0xf bank_mask:0xf
	v_add_f32_dpp v63, v64, v64 quad_perm:[2,3,0,1] row_mask:0xf bank_mask:0xf
	v_cvt_pk_bf16_f32 v61, v58, v59
	v_add_f32_dpp v56, v56, v56 row_half_mirror row_mask:0xf bank_mask:0xf
	v_add_f32_dpp v57, v57, v57 row_half_mirror row_mask:0xf bank_mask:0xf
	v_add_f32_dpp v59, v62, v62 row_half_mirror row_mask:0xf bank_mask:0xf
	v_add_f32_dpp v62, v63, v63 row_half_mirror row_mask:0xf bank_mask:0xf
	v_cvt_pk_bf16_f32 v58, v48, v49
	v_add_f32_dpp v48, v56, v56 row_mirror row_mask:0xf bank_mask:0xf
	v_add_f32_dpp v49, v57, v57 row_mirror row_mask:0xf bank_mask:0xf
	v_add_f32_dpp v57, v59, v59 row_mirror row_mask:0xf bank_mask:0xf
	v_add_f32_dpp v62, v62, v62 row_mirror row_mask:0xf bank_mask:0xf
	v_mov_b32_e32 v56, v48
	v_mov_b32_e32 v63, v49
	v_mov_b32_e32 v64, v57
	v_mov_b32_e32 v84, v62
	v_cvt_pk_bf16_f32 v59, v50, v51
	v_permlane16_swap_b32_e32 v48, v56
	v_add_f32_e32 v56, v48, v56
	v_permlane16_swap_b32_e32 v49, v63
	v_add_f32_e32 v50, v49, v63
	v_permlane16_swap_b32_e32 v57, v64
	v_add_f32_e32 v49, v57, v64
	v_permlane16_swap_b32_e32 v62, v84
	v_add_f32_e32 v48, v62, v84
	v_cvt_pk_bf16_f32 v63, v46, v47
	v_mov_b32_e32 v57, v56
	v_mov_b32_e32 v51, v50
	v_mov_b32_e32 v47, v49
	v_mov_b32_e32 v46, v48
	v_add_co_u32_e32 v84, vcc, s1, v68
	v_cvt_pk_bf16_f32 v62, v44, v45
	s_nop 0
	v_addc_co_u32_e32 v85, vcc, -1, v69, vcc
	v_lshl_add_u64 v[44:45], s[4:5], 2, v[66:67]
	v_permlane32_swap_b32_e32 v56, v57
	v_permlane32_swap_b32_e32 v50, v51
	v_permlane32_swap_b32_e32 v49, v47
	v_permlane32_swap_b32_e32 v48, v46
	global_store_dwordx2 v[84:85], v[72:73], off offset:-3584
	global_store_dwordx2 v[84:85], v[60:61], off offset:-3072
	global_store_dwordx2 v[84:85], v[58:59], off offset:-2560
	global_store_dwordx2 v[84:85], v[62:63], off offset:-2048
	s_and_saveexec_b64 s[12:13], s[2:3]
	s_cbranch_execz .LBB0_83
	s_waitcnt lgkmcnt(3)
	v_add_f32_e32 v56, v56, v57
	v_fmamk_f32 v56, v56, 0x3a800000, v82
	v_mul_f32_e32 v57, 0x4f800000, v56
	v_cmp_gt_f32_e32 vcc, s7, v56
	s_nop 1
	v_cndmask_b32_e32 v56, v56, v57, vcc
	v_sqrt_f32_e32 v57, v56
	s_nop 0
	v_add_u32_e32 v58, -1, v57
	v_fma_f32 v60, -v58, v57, v56
	v_add_u32_e32 v59, 1, v57
	v_cmp_ge_f32_e64 s[4:5], 0, v60
	s_nop 1
	v_cndmask_b32_e64 v58, v57, v58, s[4:5]
	v_fma_f32 v57, -v59, v57, v56
	v_cmp_lt_f32_e64 s[4:5], 0, v57
	s_nop 1
	v_cndmask_b32_e64 v57, v58, v59, s[4:5]
	v_mul_f32_e32 v58, 0x37800000, v57
	v_cndmask_b32_e32 v57, v57, v58, vcc
	v_cmp_class_f32_e32 vcc, v56, v83
	s_nop 1
	v_cndmask_b32_e32 v56, v57, v56, vcc
	v_div_scale_f32 v57, s[4:5], v56, v56, 1.0
	v_rcp_f32_e32 v58, v57
	s_and_b32 s4, s0, 0xffc
	v_fma_f32 v59, -v57, v58, 1.0
	v_fmac_f32_e32 v58, v59, v58
	v_div_scale_f32 v59, vcc, 1.0, v56, 1.0
	v_mul_f32_e32 v60, v59, v58
	v_fma_f32 v61, -v57, v60, v59
	v_fmac_f32_e32 v60, v61, v58
	v_fma_f32 v57, -v57, v60, v59
	v_div_fmas_f32 v57, v57, v58, v60
	v_div_fixup_f32 v58, v57, v56, 1.0
	v_lshlrev_b32_e64 v56, v75, s0
	v_and_b32_e32 v56, 0xff0, v56
	v_lshrrev_b32_e64 v59, v74, s4
	v_lshlrev_b32_e32 v64, 2, v56
	v_lshl_add_u64 v[56:57], v[44:45], 0, v[64:65]
	v_lshlrev_b32_e32 v64, 2, v59
	v_lshl_add_u64 v[56:57], v[56:57], 0, v[64:65]
	global_store_dword v[56:57], v58, off
